# SSD chunk head: redundant inline vmcnt(0) fence removed (it only waited for the previous chunk's store acks in front of the staging load batch)
# baseline (speedup 1.0000x reference)
; DI void ssd_item(const Params& p, int l, int it, char* smem) {
;     ...
;     const int pos0 = dir ? ((ci < 2) ? (1 - ci) * 128 : (CTXL + (17 - ci) * 128)) : ci * 128;
;     asm volatile("s_waitcnt vmcnt(0)" ::: "memory");
;     bf16x8 creg[8];
;     const u16* cr = XBCA + (rbase + pos0 + w * 32 + l32) * 1024 + 768 + g * 128 + h * 8;
; #pragma unroll
;     for (int ks = 0; ks < 4; ++ks) creg[ks] = *(const bf16x8*)(cr + ks * 16);
;     __builtin_amdgcn_sched_barrier(0);
; #pragma unroll
;     for (int i = 0; i < 8; ++i) {
;       const int q = tid + 256 * i, j = q >> 4, ch = q & 15;
;       *(uint4*)&BG[j * 136 + ch * 8] = *(const uint4*)&XBCA[(rbase + pos0 + j) * 1024 + 512 + g * 128 + ch * 8];
;     }
;     if (w == 0) {
;       const float r0 = DT[(rbase + pos0 + 2 * lane) * 16 + dir * 8 + hd] + dtb;
;       const float r1 = DT[(rbase + pos0 + 2 * lane + 1) * 16 + dir * 8 + hd] + dtb;
;       const float dt0 = (r0 > 20.f) ? r0 : log1pf(expf(r0));
;       const float dt1 = (r1 > 20.f) ? r1 : log1pf(expf(r1));
.LBB0_989:
	s_add_u32 s78, s81, s86
	s_addc_u32 s79, s80, 0
	v_lshl_add_u64 v[32:33], v[158:159], 0, s[78:79]
	v_lshlrev_b64 v[32:33], 11, v[32:33]
	v_lshl_add_u64 v[36:37], v[200:201], 0, v[32:33]
	global_load_dwordx4 v[32:35], v[36:37], off offset:1536
	global_load_dwordx4 v[136:139], v[36:37], off offset:1568
	global_load_dwordx4 v[132:135], v[36:37], off offset:1600
	global_load_dwordx4 v[128:131], v[36:37], off offset:1632
	v_lshl_add_u64 v[42:43], s[78:79], 0, v[162:163]
	v_lshlrev_b64 v[42:43], 11, v[42:43]
	v_lshl_add_u64 v[42:43], v[160:161], 0, v[42:43]
	global_load_dwordx4 v[64:67], v[42:43], off offset:1024
	v_lshl_add_u64 v[44:45], s[78:79], 0, v[166:167]
	v_lshlrev_b64 v[44:45], 11, v[44:45]
	v_lshl_add_u64 v[44:45], v[160:161], 0, v[44:45]
	global_load_dwordx4 v[68:71], v[44:45], off offset:1024
	v_lshl_add_u64 v[46:47], s[78:79], 0, v[170:171]
	v_lshlrev_b64 v[46:47], 11, v[46:47]
	v_lshl_add_u64 v[46:47], v[160:161], 0, v[46:47]
	global_load_dwordx4 v[72:75], v[46:47], off offset:1024
	v_lshl_add_u64 v[48:49], s[78:79], 0, v[178:179]
	v_lshlrev_b64 v[48:49], 11, v[48:49]
	v_lshl_add_u64 v[48:49], v[160:161], 0, v[48:49]
	global_load_dwordx4 v[76:79], v[48:49], off offset:1024
	v_lshl_add_u64 v[50:51], s[78:79], 0, v[182:183]
	v_lshlrev_b64 v[50:51], 11, v[50:51]
	v_lshl_add_u64 v[50:51], v[160:161], 0, v[50:51]
	global_load_dwordx4 v[80:83], v[50:51], off offset:1024
	v_lshl_add_u64 v[52:53], s[78:79], 0, v[186:187]
	v_lshlrev_b64 v[52:53], 11, v[52:53]
	v_lshl_add_u64 v[52:53], v[160:161], 0, v[52:53]
	global_load_dwordx4 v[84:87], v[52:53], off offset:1024
	v_lshl_add_u64 v[54:55], s[78:79], 0, v[190:191]
	v_lshlrev_b64 v[54:55], 11, v[54:55]
	v_lshl_add_u64 v[54:55], v[160:161], 0, v[54:55]
	global_load_dwordx4 v[88:91], v[54:55], off offset:1024
	v_lshl_add_u64 v[56:57], s[78:79], 0, v[194:195]
	v_lshlrev_b64 v[56:57], 11, v[56:57]
	v_lshl_add_u64 v[56:57], v[160:161], 0, v[56:57]
	global_load_dwordx4 v[92:95], v[56:57], off offset:1024
	s_and_saveexec_b64 s[0:1], s[38:39]
	v_lshl_add_u64 v[58:59], s[78:79], 0, v[172:173]
	v_lshlrev_b64 v[58:59], 6, v[58:59]
	v_lshl_add_u64 v[58:59], s[72:73], 0, v[58:59]
	global_load_dword v60, v[58:59], off
	global_load_dword v61, v[58:59], off offset:64
	s_or_b64 exec, exec, s[0:1]
	s_waitcnt vmcnt(0)
	ds_write_b128 v164, v[64:67]
	ds_write_b128 v168, v[68:71]
	ds_write_b128 v176, v[72:75]
	ds_write_b128 v180, v[76:79]
	ds_write_b128 v184, v[80:83]
	ds_write_b128 v188, v[84:87]
	ds_write_b128 v192, v[88:91]
	ds_write_b128 v196, v[92:95]
	s_and_saveexec_b64 s[0:1], s[38:39]
	s_cbranch_execz .LBB0_996
	v_mov_b32_e32 v40, v60
	v_mov_b32_e32 v38, v61
	v_add_f32_e32 v156, v234, v40
	v_cmp_nlt_f32_e32 vcc, s53, v156
	s_and_saveexec_b64 s[34:35], vcc
	s_cbranch_execz .LBB0_992
; DI void ssd_item(const Params& p, int l, int it, char* smem) {
;     ...
;       const float r0 = DT[(rbase + pos0 + 2 * lane) * 16 + dir * 8 + hd] + dtb;
;       const float r1 = DT[(rbase + pos0 + 2 * lane + 1) * 16 + dir * 8 + hd] + dtb;
;       const float dt0 = (r0 > 20.f) ? r0 : log1pf(expf(r0));
;       const float dt1 = (r1 > 20.f) ? r1 : log1pf(expf(r1));
;       const float a0 = dt0 * a, a1 = dt1 * a;
	v_mul_f32_e32 v39, 0x3fb8aa3b, v156
	v_rndne_f32_e32 v40, v39
	v_sub_f32_e32 v41, v39, v40
	v_fma_f32 v39, v156, s2, -v39
	v_fmac_f32_e32 v39, 0x32a5705f, v156
	v_add_f32_e32 v39, v41, v39
	v_cvt_i32_f32_e32 v40, v40
	v_exp_f32_e32 v39, v39
	v_cmp_ngt_f32_e32 vcc, s3, v156
	v_ldexp_f32 v39, v39, v40
	s_nop 0
	v_cndmask_b32_e32 v39, 0, v39, vcc
	v_cmp_nlt_f32_e32 vcc, s58, v156
	s_nop 1
	v_cndmask_b32_e32 v39, v217, v39, vcc
	v_add_f32_e32 v42, 1.0, v39
	v_add_f32_e32 v40, -1.0, v42
	v_sub_f32_e32 v41, v40, v42
	v_add_f32_e32 v41, 1.0, v41
	v_sub_f32_e32 v40, v39, v40
	v_add_f32_e32 v43, v40, v41
	v_frexp_mant_f32_e32 v44, v42
	v_cvt_f64_f32_e32 v[40:41], v42
	v_frexp_exp_i32_f64_e32 v40, v[40:41]
	v_cmp_gt_f32_e32 vcc, s14, v44
	s_nop 1
	v_subbrev_co_u32_e32 v48, vcc, 0, v40, vcc
	v_sub_u32_e32 v40, 0, v48
	v_ldexp_f32 v41, v42, v40
	v_add_f32_e32 v42, -1.0, v41
	v_add_f32_e32 v44, 1.0, v41
	v_ldexp_f32 v40, v43, v40
	v_add_f32_e32 v43, 1.0, v42
	v_add_f32_e32 v45, -1.0, v44
	v_sub_f32_e32 v43, v41, v43
	v_sub_f32_e32 v41, v41, v45
	v_add_f32_e32 v43, v40, v43
	v_add_f32_e32 v40, v40, v41
	v_add_f32_e32 v49, v44, v40
	v_rcp_f32_e32 v51, v49
	v_sub_f32_e32 v41, v44, v49
	v_add_f32_e32 v50, v40, v41
	v_add_f32_e32 v41, v42, v43
	v_mul_f32_e32 v53, v41, v51
	v_sub_f32_e32 v40, v42, v41
	v_mul_f32_e32 v42, v49, v53
	v_fma_f32 v44, v53, v49, -v42
	v_fmac_f32_e32 v44, v53, v50
	v_add_f32_e32 v52, v43, v40
	v_add_f32_e32 v40, v42, v44
	v_sub_f32_e32 v43, v41, v40
	v_pk_add_f32 v[46:47], v[40:41], v[42:43] neg_lo:[0,1] neg_hi:[0,1]
	v_mov_b32_e32 v45, v40
	v_pk_add_f32 v[40:41], v[46:47], v[44:45] neg_lo:[0,1] neg_hi:[0,1]
	v_cmp_neq_f32_e32 vcc, s59, v39
	v_add_f32_e32 v41, v52, v41
	v_add_f32_e32 v40, v40, v41
	v_add_f32_e32 v41, v43, v40
	v_mul_f32_e32 v52, v51, v41
	v_mul_f32_e32 v42, v49, v52
	v_fma_f32 v44, v52, v49, -v42
	v_fmac_f32_e32 v44, v52, v50
	v_sub_f32_e32 v43, v43, v41
	v_add_f32_e32 v49, v40, v43
	v_add_f32_e32 v40, v42, v44
	v_sub_f32_e32 v43, v41, v40
	v_pk_add_f32 v[46:47], v[40:41], v[42:43] neg_lo:[0,1] neg_hi:[0,1]
	v_mov_b32_e32 v45, v40
	v_pk_add_f32 v[40:41], v[46:47], v[44:45] neg_lo:[0,1] neg_hi:[0,1]
	s_nop 0
	v_add_f32_e32 v41, v49, v41
	v_add_f32_e32 v40, v40, v41
	v_add_f32_e32 v41, v53, v52
	v_add_f32_e32 v40, v43, v40
	v_sub_f32_e32 v42, v41, v53
	v_mul_f32_e32 v40, v51, v40
	v_sub_f32_e32 v42, v52, v42
	v_add_f32_e32 v42, v42, v40
	v_add_f32_e32 v44, v41, v42
	v_mul_f32_e32 v45, v44, v44
	v_fmamk_f32 v40, v45, 0x3e9b6dac, v205
	v_fmaak_f32 v175, v45, v40, 0x3f2aaada
	v_cvt_f32_i32_e32 v40, v48
	v_sub_f32_e32 v41, v44, v41
	v_sub_f32_e32 v41, v42, v41
	v_ldexp_f32 v46, v41, 1
	v_mul_f32_e32 v41, v44, v45
	v_ldexp_f32 v43, v44, 1
	v_pk_mul_f32 v[44:45], v[40:41], v[174:175]
	s_nop 0
	v_fma_f32 v42, v40, s15, -v44
	v_fmac_f32_e32 v42, 0xb102e308, v40
	v_pk_add_f32 v[40:41], v[44:45], v[42:43]
	s_nop 0
	v_sub_f32_e32 v43, v41, v43
	v_sub_f32_e32 v43, v45, v43
	v_add_f32_e32 v47, v46, v43
	v_mov_b32_e32 v46, v44
	v_pk_add_f32 v[44:45], v[40:41], v[44:45] neg_lo:[0,1] neg_hi:[0,1]
	v_pk_add_f32 v[48:49], v[40:41], v[46:47]
	v_mov_b32_e32 v43, v40
	v_mov_b32_e32 v45, v49
	v_pk_add_f32 v[50:51], v[42:43], v[44:45] neg_lo:[0,1] neg_hi:[0,1]
	v_pk_add_f32 v[42:43], v[42:43], v[44:45]
	v_mov_b32_e32 v46, v47
	v_pk_add_f32 v[44:45], v[42:43], v[40:41] op_sel:[1,0] op_sel_hi:[0,1] neg_lo:[0,1] neg_hi:[0,1]
	v_pk_add_f32 v[52:53], v[48:49], v[44:45] op_sel_hi:[1,0] neg_lo:[0,1] neg_hi:[0,1]
	v_mov_b32_e32 v48, v49
	v_mov_b32_e32 v49, v43
	v_pk_mov_b32 v[44:45], v[40:41], v[44:45] op_sel:[1,0]
	v_mov_b32_e32 v47, v40
	v_pk_add_f32 v[44:45], v[48:49], v[44:45] neg_lo:[0,1] neg_hi:[0,1]
	v_mov_b32_e32 v52, v50
	v_pk_add_f32 v[40:41], v[46:47], v[44:45] neg_lo:[0,1] neg_hi:[0,1]
	v_mov_b32_e32 v51, v43
	v_pk_add_f32 v[44:45], v[52:53], v[40:41]
	s_nop 0
	v_pk_add_f32 v[46:47], v[44:45], v[44:45] op_sel:[0,1] op_sel_hi:[1,0]
	s_nop 0
	v_pk_add_f32 v[42:43], v[42:43], v[46:47] op_sel:[1,0] op_sel_hi:[0,1]
	v_mov_b32_e32 v45, v42
	v_pk_add_f32 v[48:49], v[44:45], v[50:51] neg_lo:[0,1] neg_hi:[0,1]
	v_mov_b32_e32 v41, v46
	v_sub_f32_e32 v43, v44, v48
	v_pk_add_f32 v[40:41], v[40:41], v[48:49] neg_lo:[0,1] neg_hi:[0,1]
	v_sub_f32_e32 v43, v50, v43
	v_add_f32_e32 v40, v40, v43
	v_add_f32_e32 v40, v40, v41
	v_add_f32_e32 v40, v42, v40
	v_cndmask_b32_e32 v40, v217, v40, vcc
	v_cmp_lt_f32_e64 vcc, |v39|, s12
	s_nop 1
	v_cndmask_b32_e32 v156, v40, v39, vcc
